# P8 work queue order: attention pieces first (big-first), stencil tiles second, SGU items last (was stencil first)
# baseline (speedup 1.0000x reference)
; __device__ __forceinline__ void phase_moba_attn(const Params& P, LAS unsigned char* lds, int l, int qslot) {
;     ...
;         const unsigned x = y < 128u ? 896u + y : y - 128u;
;         if (tid == 0) nextx = __hip_atomic_fetch_add(qctr, 1u, __ATOMIC_RELAXED, __HIP_MEMORY_SCOPE_AGENT);
;         if (x >= 384u) {
;             if (x < 896u) sgu_item(P, lds, l, (int)(x - 384u));
;             else { const int tile = (int)(x - 896u) * 8 + wave; if (tile < 512) pool_tile(P, l, tile, lane); else conv_tile(P, l, tile - 512, lane); }
;             continue;
;         }
;         const int bh = (int)(x & 15u), rr = (int)(x >> 4);
;         const unsigned ent = (unsigned)((rr < 12 ? (TA >> (5 * rr)) : (TB >> (5 * (rr - 12)))) & 31ull);
;         const int i = (int)(ent & 15u), sp = (int)(ent >> 4);
;         int jlo = 0, jhi = i;
;         if (i >= 8) { const int h1 = (i + 1) >> 1; if (sp == 0) jhi = h1 - 1; else jlo = h1; }
;         const int nch = 4 * (jhi - jlo + 1);
;         const int t0 = 256 * i, tq = t0 + 32 * wave + ln, tql = 32 * wave + ln;
;         { const f32x4 v = *(const f32x4*)(kmean + (size_t)bh * NBLK * HD + 4 * tid); *(LAS f32x4*)(km + 4 * tid) = v; }
;         f16x8 qf[8];
;         { const f16* qrow = Q16 + ((size_t)bh * SEQ + tq) * HD + 8 * hf;
; #pragma unroll
;             for (int st = 0; st < 8; ++st) qf[st] = *(const f16x8*)(qrow + 16 * st); }
;         __syncthreads();
;         unsigned mask = 0u;
;         if (i <= 3) mask = (1u << i) - 1u;
;         else {
;             float v0 = -INFINITY, v1 = -INFINITY, v2 = -INFINITY; int i0 = 0, i1 = 0, i2 = 0;
; #pragma unroll 1
;             for (int j = 0; j < i; ++j) {
;                 const LAS float* kr = km + j * HD + 8 * hf;
;                 float a = 0.f;
; #pragma unroll
;                 for (int st = 0; st < 8; ++st) { const f32x4 k0 = *(const LAS f32x4*)(kr + 16 * st), k1 = *(const LAS f32x4*)(kr + 16 * st + 4);
;                     a = fmaf((float)qf[st][0], k0[0], a); a = fmaf((float)qf[st][1], k0[1], a); a = fmaf((float)qf[st][2], k0[2], a); a = fmaf((float)qf[st][3], k0[3], a);
;                     a = fmaf((float)qf[st][4], k1[0], a); a = fmaf((float)qf[st][5], k1[1], a); a = fmaf((float)qf[st][6], k1[2], a); a = fmaf((float)qf[st][7], k1[3], a); }
;                 const float b2 = __shfl_xor(a, 32);
;                 const float x2 = (hf == 0) ? (a + b2) : (b2 + a);
.LBB0_893:
	s_or_b64 exec, exec, s[0:1]
	s_add_i32 s63, s2, 0xffffff80
	s_add_i32 s0, s2, 0x200
	s_cmpk_lt_u32 s2, 0x200
	s_cselect_b32 s63, s0, s63
	s_cmpk_lt_u32 s2, 0x180
	s_cselect_b32 s63, s2, s63
	s_cmpk_lt_u32 s63, 0x180
	s_mov_b64 s[0:1], -1
	s_cbranch_scc0 .LBB0_925
	v_mov_b32_e32 v245, 0x14000
	v_lshl_add_u32 v245, v0, 2, v245
	ds_write_b32 v245, v192 offset:0
	ds_write_b32 v245, v193 offset:2048
	ds_write_b32 v245, v194 offset:4096
	ds_write_b32 v245, v195 offset:6144
	ds_write_b32 v245, v196 offset:8192
	ds_write_b32 v245, v197 offset:10240
	ds_write_b32 v245, v198 offset:12288
	ds_write_b32 v245, v199 offset:14336
	ds_write_b32 v245, v200 offset:16384
	ds_write_b32 v245, v201 offset:18432
	ds_write_b32 v245, v202 offset:20480
	ds_write_b32 v245, v203 offset:22528
	ds_write_b32 v245, v204 offset:24576
	ds_write_b32 v245, v205 offset:26624
	ds_write_b32 v245, v206 offset:28672
	s_waitcnt lgkmcnt(0)
	s_and_b32 s19, s2, 15
	s_lshr_b32 s2, s63, 4
	s_cmpk_lt_u32 s63, 0xc0
	s_mul_i32 s2, s2, 5
	s_cselect_b64 s[0:1], -1, 0
	s_sub_i32 s3, s2, 60
	s_and_b64 s[0:1], s[0:1], exec
	s_mov_b32 s0, 0xdad86e7
	s_cselect_b32 s1, s0, 0x44341
	s_mov_b32 s0, 0x5ae3fbef
	s_cselect_b32 s2, s2, s3
	s_cselect_b32 s0, s0, 0x3194a8ba
	s_lshl_b32 s56, s19, 13
	v_lshl_add_u64 v[4:5], v[162:163], 0, s[56:57]
	global_load_dwordx4 v[4:7], v[4:5], off
	s_lshr_b64 s[8:9], s[0:1], s2
	s_and_b32 s3, s8, 15
	s_lshl_b32 s2, s3, 8
	v_add_u32_e32 v8, s2, v219
	s_lshl_b32 s0, s19, 12
	s_mov_b32 s1, s57
	v_ashrrev_i32_e32 v9, 31, v8
	v_lshl_add_u64 v[214:215], s[0:1], 0, v[8:9]
	s_mov_b64 s[12:13], -1
	s_cmp_lt_u32 s3, 4
	s_waitcnt vmcnt(0)
	ds_write_b128 v220, v[4:7]
	v_lshlrev_b64 v[4:5], 8, v[214:215]
	v_lshl_add_u64 v[4:5], v[166:167], 0, v[4:5]
	global_load_dwordx4 v[98:101], v[4:5], off
	global_load_dwordx4 v[102:105], v[4:5], off offset:32
	global_load_dwordx4 v[106:109], v[4:5], off offset:64
	global_load_dwordx4 v[110:113], v[4:5], off offset:96
	global_load_dwordx4 v[114:117], v[4:5], off offset:128
	global_load_dwordx4 v[118:121], v[4:5], off offset:160
	global_load_dwordx4 v[122:125], v[4:5], off offset:192
	global_load_dwordx4 v[126:129], v[4:5], off offset:224
	s_waitcnt lgkmcnt(0)
	s_barrier
	s_cbranch_scc1 .LBB0_905
	v_and_b32_e32 v4, 64, v238
	v_xor_b32_e32 v2, 32, v238
	v_add_u32_e32 v4, 64, v4
	v_cmp_lt_i32_e32 vcc, v2, v4
	s_waitcnt vmcnt(7)
	v_cvt_f32_f16_e32 v4, v98
	v_cvt_f32_f16_sdwa v5, v98 dst_sel:DWORD dst_unused:UNUSED_PAD src0_sel:WORD_1
	v_cvt_f32_f16_e32 v6, v99
	v_cvt_f32_f16_sdwa v7, v99 dst_sel:DWORD dst_unused:UNUSED_PAD src0_sel:WORD_1
	v_cvt_f32_f16_e32 v8, v100
	v_cvt_f32_f16_sdwa v9, v100 dst_sel:DWORD dst_unused:UNUSED_PAD src0_sel:WORD_1
	v_cvt_f32_f16_e32 v10, v101
	v_cvt_f32_f16_sdwa v11, v101 dst_sel:DWORD dst_unused:UNUSED_PAD src0_sel:WORD_1
	s_waitcnt vmcnt(6)
	v_cvt_f32_f16_e32 v12, v102
	v_cvt_f32_f16_sdwa v13, v102 dst_sel:DWORD dst_unused:UNUSED_PAD src0_sel:WORD_1
	v_cvt_f32_f16_e32 v14, v103
	v_cvt_f32_f16_sdwa v15, v103 dst_sel:DWORD dst_unused:UNUSED_PAD src0_sel:WORD_1
	v_cvt_f32_f16_e32 v16, v104
	v_cvt_f32_f16_sdwa v17, v104 dst_sel:DWORD dst_unused:UNUSED_PAD src0_sel:WORD_1
	v_cvt_f32_f16_e32 v18, v105
	v_cvt_f32_f16_sdwa v19, v105 dst_sel:DWORD dst_unused:UNUSED_PAD src0_sel:WORD_1
	s_waitcnt vmcnt(5)
	v_cvt_f32_f16_e32 v20, v106
	v_cvt_f32_f16_sdwa v21, v106 dst_sel:DWORD dst_unused:UNUSED_PAD src0_sel:WORD_1
	v_cvt_f32_f16_e32 v22, v107
	v_cvt_f32_f16_sdwa v23, v107 dst_sel:DWORD dst_unused:UNUSED_PAD src0_sel:WORD_1
	v_cvt_f32_f16_e32 v24, v108
	v_cvt_f32_f16_sdwa v25, v108 dst_sel:DWORD dst_unused:UNUSED_PAD src0_sel:WORD_1
	v_cvt_f32_f16_e32 v26, v109
	v_cvt_f32_f16_sdwa v27, v109 dst_sel:DWORD dst_unused:UNUSED_PAD src0_sel:WORD_1
	s_waitcnt vmcnt(4)
	v_cvt_f32_f16_e32 v28, v110
	v_cvt_f32_f16_sdwa v29, v110 dst_sel:DWORD dst_unused:UNUSED_PAD src0_sel:WORD_1
	v_cvt_f32_f16_e32 v30, v111
	v_cvt_f32_f16_sdwa v31, v111 dst_sel:DWORD dst_unused:UNUSED_PAD src0_sel:WORD_1
	v_cvt_f32_f16_e32 v32, v112
	v_cvt_f32_f16_sdwa v33, v112 dst_sel:DWORD dst_unused:UNUSED_PAD src0_sel:WORD_1
	v_cvt_f32_f16_e32 v34, v113
	v_cvt_f32_f16_sdwa v35, v113 dst_sel:DWORD dst_unused:UNUSED_PAD src0_sel:WORD_1
	s_waitcnt vmcnt(3)
	v_cvt_f32_f16_e32 v36, v114
	v_cvt_f32_f16_sdwa v37, v114 dst_sel:DWORD dst_unused:UNUSED_PAD src0_sel:WORD_1
	v_cvt_f32_f16_e32 v38, v115
	v_cvt_f32_f16_sdwa v39, v115 dst_sel:DWORD dst_unused:UNUSED_PAD src0_sel:WORD_1
	v_cvt_f32_f16_e32 v40, v116
	v_cvt_f32_f16_sdwa v41, v116 dst_sel:DWORD dst_unused:UNUSED_PAD src0_sel:WORD_1
	v_cvt_f32_f16_e32 v42, v117
	v_cvt_f32_f16_sdwa v43, v117 dst_sel:DWORD dst_unused:UNUSED_PAD src0_sel:WORD_1
	s_waitcnt vmcnt(2)
	v_cvt_f32_f16_e32 v44, v118
	v_cvt_f32_f16_sdwa v45, v118 dst_sel:DWORD dst_unused:UNUSED_PAD src0_sel:WORD_1
	v_cvt_f32_f16_e32 v46, v119
	v_cvt_f32_f16_sdwa v47, v119 dst_sel:DWORD dst_unused:UNUSED_PAD src0_sel:WORD_1
	v_cvt_f32_f16_e32 v48, v120
	v_cvt_f32_f16_sdwa v49, v120 dst_sel:DWORD dst_unused:UNUSED_PAD src0_sel:WORD_1
	v_cvt_f32_f16_e32 v50, v121
	v_cvt_f32_f16_sdwa v51, v121 dst_sel:DWORD dst_unused:UNUSED_PAD src0_sel:WORD_1
	s_waitcnt vmcnt(1)
	v_cvt_f32_f16_e32 v52, v122
	v_cvt_f32_f16_sdwa v53, v122 dst_sel:DWORD dst_unused:UNUSED_PAD src0_sel:WORD_1
	v_cvt_f32_f16_e32 v54, v123
	v_cvt_f32_f16_sdwa v55, v123 dst_sel:DWORD dst_unused:UNUSED_PAD src0_sel:WORD_1
	v_cvt_f32_f16_e32 v56, v124
	v_cvt_f32_f16_sdwa v57, v124 dst_sel:DWORD dst_unused:UNUSED_PAD src0_sel:WORD_1
	v_cvt_f32_f16_e32 v58, v125
	v_cvt_f32_f16_sdwa v59, v125 dst_sel:DWORD dst_unused:UNUSED_PAD src0_sel:WORD_1
	s_waitcnt vmcnt(0)
	v_cvt_f32_f16_e32 v60, v126
	v_cvt_f32_f16_sdwa v61, v126 dst_sel:DWORD dst_unused:UNUSED_PAD src0_sel:WORD_1
	v_cvt_f32_f16_e32 v62, v127
	v_cvt_f32_f16_sdwa v63, v127 dst_sel:DWORD dst_unused:UNUSED_PAD src0_sel:WORD_1
	v_cvt_f32_f16_e32 v64, v128
	v_cvt_f32_f16_sdwa v65, v128 dst_sel:DWORD dst_unused:UNUSED_PAD src0_sel:WORD_1
	v_cvt_f32_f16_e32 v66, v129
	v_cvt_f32_f16_sdwa v67, v129 dst_sel:DWORD dst_unused:UNUSED_PAD src0_sel:WORD_1
	v_cndmask_b32_e32 v2, v238, v2, vcc
	s_mov_b32 s1, 0
	v_lshlrev_b32_e32 v2, 2, v2
	s_lshl_b32 s9, s3, 9
	v_mov_b32_e32 v69, 0xff800000
	v_mov_b32_e32 v71, 0
	v_mov_b32_e32 v68, 0
	v_mov_b32_e32 v72, 0
	v_mov_b32_e32 v70, 0xff800000
	v_mov_b32_e32 v73, 0xff800000
	s_mov_b32 s18, 0
